# rwkv_prep: 32 weight-row loads of the low-rank projections batched per sub-tile with counted waits (was load/wait/MFMA ladder)
# baseline (speedup 1.0000x reference)
; __device__ __forceinline__ void rwkv_prep_task(KP p, int l, int tile, int hg, bf16_t* sAp) {
;     ...
;     const int h = hg * 4 + wid;
;     bf16x8 af[8];
; #pragma unroll
;     for (int ks = 0; ks < 8; ++ks) af[ks] = *(const bf16x8*)(sAp + fr * 264 + ks * 32 + fq * 8);
;     const bf16_t* WupT = (const bf16_t*)(p->ws + OFF_WUP);
;     const bf16_t* AupT = (const bf16_t*)(p->ws + OFF_AUP);
;     const bf16_t* GupT = (const bf16_t*)(p->ws + OFF_GUP);
;     f32x4 az[4], aa[4], ag[4];
; #pragma unroll
;     for (int nt = 0; nt < 4; ++nt) {
;         const int n = h * 64 + fr * 4 + nt;
;         f32x4 z = {0.f, 0.f, 0.f, 0.f};
;         z = __builtin_amdgcn_mfma_f32_16x16x32_bf16(*(const bf16x8*)(WupT + n * 64 + fq * 8), af[0], z, 0, 0, 0);
;         z = __builtin_amdgcn_mfma_f32_16x16x32_bf16(*(const bf16x8*)(WupT + n * 64 + 32 + fq * 8), af[1], z, 0, 0, 0);
;         az[nt] = z;
;         f32x4 a = {0.f, 0.f, 0.f, 0.f};
;         a = __builtin_amdgcn_mfma_f32_16x16x32_bf16(*(const bf16x8*)(AupT + n * 64 + fq * 8), af[2], a, 0, 0, 0);
;         a = __builtin_amdgcn_mfma_f32_16x16x32_bf16(*(const bf16x8*)(AupT + n * 64 + 32 + fq * 8), af[3], a, 0, 0, 0);
;         aa[nt] = a;
;         f32x4 g = {0.f, 0.f, 0.f, 0.f};
; #pragma unroll
;         for (int ks = 0; ks < 4; ++ks)
;             g = __builtin_amdgcn_mfma_f32_16x16x32_bf16(*(const bf16x8*)(GupT + n * 128 + ks * 32 + fq * 8), af[4 + ks], g, 0, 0, 0);
;         ag[nt] = g;
;     }
.LBB0_415:
	s_or_b64 exec, exec, s[12:13]
	v_ashrrev_i32_e32 v2, 6, v72
	s_and_b32 s2, s11, 4
	v_bfe_u32 v3, v1, 16, 1
	v_bfe_u32 v153, v72, 4, 2
	v_add_u32_e32 v152, s2, v2
	v_and_b32_e32 v73, 15, v72
	v_add3_u32 v1, v1, v3, s72
	v_lshlrev_b32_e32 v12, 4, v153
	s_movk_i32 s12, 0x210
	v_lshlrev_b32_e32 v74, 6, v152
	ds_write_b16_d16_hi v0, v1 offset:7920
	v_mad_u32_u24 v0, v73, s12, v12
	v_lshl_or_b32 v75, v73, 2, v74
	s_waitcnt lgkmcnt(0)
	s_barrier
	ds_read_b128 v[66:69], v0
	ds_read_b128 v[46:49], v0 offset:64
	ds_read_b128 v[62:65], v0 offset:128
	ds_read_b128 v[42:45], v0 offset:192
	ds_read_b128 v[58:61], v0 offset:256
	ds_read_b128 v[54:57], v0 offset:320
	ds_read_b128 v[50:53], v0 offset:384
	ds_read_b128 v[38:41], v0 offset:448
	v_or_b32_e32 v154, s39, v73
	s_mov_b64 s[42:43], -1
	s_and_b64 vcc, exec, s[78:79]
	v_lshl_add_u32 v71, v75, 8, v12
	v_lshl_add_u32 v70, v75, 7, v12
	global_load_dwordx4 v[14:17], v70, s[46:47]
	global_load_dwordx4 v[76:79], v70, s[46:47] offset:64
	global_load_dwordx4 v[8:11], v70, s[48:49]
	global_load_dwordx4 v[80:83], v70, s[48:49] offset:64
	global_load_dwordx4 v[0:3], v71, s[50:51]
	global_load_dwordx4 v[236:239], v71, s[50:51] offset:64
	global_load_dwordx4 v[240:243], v71, s[50:51] offset:128
	global_load_dwordx4 v[244:247], v71, s[50:51] offset:192
	v_or_b32_e32 v70, 1, v75
	v_lshl_add_u32 v71, v70, 8, v12
	v_lshl_add_u32 v70, v70, 7, v12
	global_load_dwordx4 v[22:25], v70, s[46:47]
	global_load_dwordx4 v[18:21], v70, s[48:49]
	global_load_dwordx4 v[4:7], v71, s[50:51]
	global_load_dwordx4 v[248:251], v70, s[46:47] offset:64
	global_load_dwordx4 v[252:255], v70, s[48:49] offset:64
	s_waitcnt vmcnt(5) lgkmcnt(0)
	v_mfma_f32_16x16x32_bf16 v[14:17], v[14:17], v[66:69], 0
	v_mfma_f32_16x16x32_bf16 v[8:11], v[8:11], v[62:65], 0
	v_mfma_f32_16x16x32_bf16 v[0:3], v[0:3], v[58:61], 0
	v_mfma_f32_16x16x32_bf16 v[14:17], v[76:79], v[46:49], v[14:17]
	v_mfma_f32_16x16x32_bf16 v[8:11], v[80:83], v[42:45], v[8:11]
	v_mfma_f32_16x16x32_bf16 v[0:3], v[236:239], v[54:57], v[0:3]
	v_mfma_f32_16x16x32_bf16 v[0:3], v[240:243], v[50:53], v[0:3]
	v_mfma_f32_16x16x32_bf16 v[0:3], v[244:247], v[38:41], v[0:3]
	s_nop 7
	s_nop 7
	global_load_dwordx4 v[76:79], v71, s[50:51] offset:64
	global_load_dwordx4 v[80:83], v71, s[50:51] offset:128
	global_load_dwordx4 v[236:239], v71, s[50:51] offset:192
	v_or_b32_e32 v70, 2, v75
	v_lshl_add_u32 v71, v70, 8, v12
	v_lshl_add_u32 v70, v70, 7, v12
	global_load_dwordx4 v[34:37], v70, s[46:47]
	global_load_dwordx4 v[30:33], v70, s[48:49]
	global_load_dwordx4 v[26:29], v71, s[50:51]
	global_load_dwordx4 v[240:243], v70, s[46:47] offset:64
	global_load_dwordx4 v[244:247], v70, s[48:49] offset:64
	s_waitcnt vmcnt(5)
	v_mfma_f32_16x16x32_bf16 v[22:25], v[22:25], v[66:69], 0
	v_mfma_f32_16x16x32_bf16 v[18:21], v[18:21], v[62:65], 0
	v_mfma_f32_16x16x32_bf16 v[4:7], v[4:7], v[58:61], 0
	v_mfma_f32_16x16x32_bf16 v[22:25], v[248:251], v[46:49], v[22:25]
	v_mfma_f32_16x16x32_bf16 v[18:21], v[252:255], v[42:45], v[18:21]
	v_mfma_f32_16x16x32_bf16 v[4:7], v[76:79], v[54:57], v[4:7]
	v_mfma_f32_16x16x32_bf16 v[4:7], v[80:83], v[50:53], v[4:7]
	v_mfma_f32_16x16x32_bf16 v[4:7], v[236:239], v[38:41], v[4:7]
	s_nop 7
	s_nop 7
	global_load_dwordx4 v[248:251], v71, s[50:51] offset:64
	global_load_dwordx4 v[252:255], v71, s[50:51] offset:128
	global_load_dwordx4 v[76:79], v71, s[50:51] offset:192
	v_or_b32_e32 v70, 3, v75
	v_lshl_add_u32 v71, v70, 8, v12
	v_lshl_add_u32 v70, v70, 7, v12
	global_load_dwordx4 v[80:83], v70, s[46:47]
	global_load_dwordx4 v[236:239], v70, s[46:47] offset:64
	s_waitcnt vmcnt(2)
	v_mfma_f32_16x16x32_bf16 v[34:37], v[34:37], v[66:69], 0
	v_mfma_f32_16x16x32_bf16 v[30:33], v[30:33], v[62:65], 0
	v_mfma_f32_16x16x32_bf16 v[26:29], v[26:29], v[58:61], 0
	v_mfma_f32_16x16x32_bf16 v[34:37], v[240:243], v[46:49], v[34:37]
	v_mfma_f32_16x16x32_bf16 v[30:33], v[244:247], v[42:45], v[30:33]
	v_mfma_f32_16x16x32_bf16 v[26:29], v[248:251], v[54:57], v[26:29]
	v_mfma_f32_16x16x32_bf16 v[26:29], v[252:255], v[50:53], v[26:29]
	v_mfma_f32_16x16x32_bf16 v[26:29], v[76:79], v[38:41], v[26:29]
	s_nop 7
	s_nop 7
	global_load_dwordx4 v[240:243], v70, s[48:49]
	global_load_dwordx4 v[244:247], v70, s[48:49] offset:64
	global_load_dwordx4 v[248:251], v71, s[50:51]
	global_load_dwordx4 v[252:255], v71, s[50:51] offset:64
	global_load_dwordx4 v[76:79], v71, s[50:51] offset:128
	s_waitcnt vmcnt(5)
	v_mfma_f32_16x16x32_bf16 v[66:69], v[80:83], v[66:69], 0
	s_nop 7
	s_nop 7
	s_nop 7
	v_mfma_f32_16x16x32_bf16 v[46:49], v[236:239], v[46:49], v[66:69]
	s_nop 7
	s_nop 7
	global_load_dwordx4 v[80:83], v71, s[50:51] offset:192
	s_waitcnt vmcnt(4)
	v_mfma_f32_16x16x32_bf16 v[62:65], v[240:243], v[62:65], 0
	s_nop 7
	s_nop 7
	s_nop 7
	v_mfma_f32_16x16x32_bf16 v[42:45], v[244:247], v[42:45], v[62:65]
	s_waitcnt vmcnt(1)
	v_mfma_f32_16x16x32_bf16 v[58:61], v[248:251], v[58:61], 0
	s_nop 7
	s_nop 7
	s_nop 7
	v_mfma_f32_16x16x32_bf16 v[54:57], v[252:255], v[54:57], v[58:61]
	s_nop 7
	s_nop 7
	s_nop 7
	v_mfma_f32_16x16x32_bf16 v[50:53], v[76:79], v[50:53], v[54:57]
	s_nop 7
	s_nop 7
	s_nop 7
	s_waitcnt vmcnt(0)
	v_mfma_f32_16x16x32_bf16 v[38:41], v[80:83], v[38:41], v[50:53]
	s_nop 7
	s_nop 7
	s_nop 7
	s_cbranch_vccz .LBB0_417
	s_nop 1
	v_add_u32_e32 v50, 0xffffc000, v154
	v_ashrrev_i32_e32 v50, 3, v50
	s_movk_i32 s2, 0x700
	v_and_b32_e32 v92, 7, v72
	v_mad_i64_i32 v[50:51], s[12:13], v50, s2, 0
	s_mov_b64 s[42:43], 0
